# GEMM tile boundary: dropped the vmcnt(0) drain before the next tile's first LDS-DMA group (older stores only make the counted waits stricter)
# baseline (speedup 1.0000x reference)
.LBB0_317:
	s_ashr_i32 s2, s4, 3
	s_add_i32 s2, s6, s2
	s_ashr_i32 s3, s2, 31
	s_lshr_b32 s3, s3, 25
	s_add_i32 s3, s2, s3
	s_and_b32 s4, s3, 0xff80
	s_sub_i32 s2, s2, s4
	s_bfe_i32 s4, s2, 0x80000
	s_bfe_u32 s4, s4, 0x3000c
	s_add_i32 s4, s2, s4
	s_bfe_i32 s5, s4, 0x80000
	s_and_b32 s4, s4, 0xf8
	s_sub_i32 s2, s2, s4
	s_sext_i32_i8 s2, s2
	s_lshl_b32 s3, s3, 4
	s_sext_i32_i16 s5, s5
	s_and_b32 s3, s3, 0xfffff800
	s_lshl_b32 s2, s2, 8
	s_add_i32 s2, s2, s3
	s_lshl_b32 s3, s5, 5
	s_and_b32 s4, s3, 0xffffff00
	s_ashr_i32 s5, s4, 31
	s_lshl_b64 s[6:7], s[4:5], 12
	s_add_u32 s6, s21, s6
	s_addc_u32 s7, s22, s7
	s_ashr_i32 s3, s2, 31
	s_lshl_b64 s[14:15], s[2:3], 12
	s_add_u32 s8, s19, s14
	s_addc_u32 s9, s20, s15
	s_or_b32 s10, s4, 0x80
	s_ashr_i32 s11, s10, 31
	s_mov_b32 m0, s24
	s_nop 0
	global_load_lds_dwordx4 v0, s[6:7]
	s_lshl_b64 s[10:11], s[10:11], 12
	s_mov_b32 m0, s25
	s_nop 0
	global_load_lds_dwordx4 v134, s[6:7]
	s_add_u32 s12, s21, s10
	s_mov_b32 m0, s23
	s_nop 0
	global_load_lds_dwordx4 v0, s[8:9]
	s_addc_u32 s13, s22, s11
	s_or_b32 s10, s2, 0x80
	s_mov_b32 m0, s26
	s_nop 0
	global_load_lds_dwordx4 v134, s[8:9]
	s_ashr_i32 s11, s10, 31
	s_mov_b32 m0, s27
	s_nop 0
	global_load_lds_dwordx4 v0, s[12:13]
	s_lshl_b64 s[10:11], s[10:11], 12
	s_mov_b32 m0, s28
	s_nop 0
	global_load_lds_dwordx4 v134, s[12:13]
	s_add_u32 s10, s19, s10
	s_addc_u32 s11, s20, s11
	s_mov_b32 m0, s29
	s_nop 0
	global_load_lds_dwordx4 v0, s[10:11]
	s_mov_b32 m0, s30
	s_nop 0
	global_load_lds_dwordx4 v134, s[10:11]
	s_and_saveexec_b64 s[16:17], s[38:39]
	s_cbranch_execz .LBB0_319
	s_barrier

.LBB0_502:
	s_ashr_i32 s4, s6, 3
	s_add_i32 s4, s8, s4
	s_ashr_i32 s5, s4, 31
	s_lshr_b32 s5, s5, 24
	s_add_i32 s5, s4, s5
	s_and_b32 s6, s5, 0xff00
	s_sub_i32 s4, s4, s6
	s_sext_i32_i16 s6, s4
	s_bfe_u32 s6, s6, 0x3001c
	s_add_i32 s6, s4, s6
	s_sext_i32_i16 s7, s6
	s_and_b32 s6, s6, 0xfff8
	s_sub_i32 s4, s4, s6
	s_sext_i32_i16 s4, s4
	s_lshl_b32 s5, s5, 3
	s_and_b32 s5, s5, 0xfffff800
	s_lshl_b32 s4, s4, 8
	s_add_i32 s4, s4, s5
	s_lshl_b32 s5, s7, 5
	s_and_b32 s6, s5, 0xffffff00
	s_ashr_i32 s7, s6, 31
	s_lshl_b64 s[8:9], s[6:7], 12
	s_add_u32 s8, s23, s8
	s_addc_u32 s9, s24, s9
	s_ashr_i32 s5, s4, 31
	s_lshl_b64 s[16:17], s[4:5], 12
	s_add_u32 s10, s21, s16
	s_addc_u32 s11, s22, s17
	s_or_b32 s12, s6, 0x80
	s_ashr_i32 s13, s12, 31
	s_mov_b32 m0, s26
	s_nop 0
	global_load_lds_dwordx4 v138, s[8:9]
	s_lshl_b64 s[12:13], s[12:13], 12
	s_mov_b32 m0, s27
	s_nop 0
	global_load_lds_dwordx4 v139, s[8:9]
	s_add_u32 s14, s23, s12
	s_mov_b32 m0, s25
	s_nop 0
	global_load_lds_dwordx4 v138, s[10:11]
	s_addc_u32 s15, s24, s13
	s_or_b32 s12, s4, 0x80
	s_mov_b32 m0, s28
	s_nop 0
	global_load_lds_dwordx4 v139, s[10:11]
	s_ashr_i32 s13, s12, 31
	s_mov_b32 m0, s29
	s_nop 0
	global_load_lds_dwordx4 v138, s[14:15]
	s_lshl_b64 s[12:13], s[12:13], 12
	s_mov_b32 m0, s30
	s_nop 0
	global_load_lds_dwordx4 v139, s[14:15]
	s_add_u32 s12, s21, s12
	s_addc_u32 s13, s22, s13
	s_mov_b32 m0, s31
	s_nop 0
	global_load_lds_dwordx4 v138, s[12:13]
	s_mov_b32 m0, s34
	s_nop 0
	global_load_lds_dwordx4 v139, s[12:13]
	s_and_saveexec_b64 s[18:19], s[38:39]
	s_cbranch_execz .LBB0_504
	s_barrier

.LBB0_591:
	s_ashr_i32 s4, s20, 31
	s_lshr_b32 s4, s4, 29
	s_add_i32 s4, s20, s4
	s_ashr_i32 s5, s4, 3
	s_and_b32 s4, s4, -8
	s_sub_i32 s4, s20, s4
	s_cmp_lt_i32 s4, 0
	s_movk_i32 s6, 0x61
	s_cselect_b32 s6, s6, 0x60
	s_mul_i32 s4, s6, s4
	s_add_i32 s4, s4, s5
	s_mul_hi_i32 s5, s4, 0x2aaaaaab
	s_lshr_b32 s6, s5, 31
	s_ashr_i32 s5, s5, 4
	s_add_i32 s5, s5, s6
	s_mul_i32 s6, s5, 0x60
	s_sub_i32 s4, s4, s6
	s_bfe_i32 s6, s4, 0x80000
	s_bfe_u32 s6, s6, 0x3000c
	s_add_i32 s6, s4, s6
	s_bfe_i32 s7, s6, 0x80000
	s_and_b32 s6, s6, 0xf8
	s_sub_i32 s4, s4, s6
	s_sext_i32_i16 s50, s7
	s_sext_i32_i8 s4, s4
	s_ashr_i32 s49, s50, 3
	s_lshl_b32 s5, s5, 11
	s_lshl_b32 s4, s4, 8
	s_add_i32 s6, s4, s5
	s_lshl_b32 s4, s49, 8
	s_ashr_i32 s5, s4, 31
	s_lshl_b64 s[8:9], s[4:5], 12
	s_add_u32 s8, s23, s8
	s_addc_u32 s9, s24, s9
	s_ashr_i32 s7, s6, 31
	s_lshl_b64 s[16:17], s[6:7], 12
	s_add_u32 s10, s21, s16
	s_addc_u32 s11, s22, s17
	s_or_b32 s12, s4, 0x80
	s_ashr_i32 s13, s12, 31
	s_mov_b32 m0, s26
	s_nop 0
	global_load_lds_dwordx4 v132, s[8:9]
	s_lshl_b64 s[12:13], s[12:13], 12
	s_mov_b32 m0, s27
	s_nop 0
	global_load_lds_dwordx4 v133, s[8:9]
	s_add_u32 s14, s23, s12
	s_mov_b32 m0, s25
	s_nop 0
	global_load_lds_dwordx4 v132, s[10:11]
	s_addc_u32 s15, s24, s13
	s_or_b32 s12, s6, 0x80
	s_mov_b32 m0, s28
	s_nop 0
	global_load_lds_dwordx4 v133, s[10:11]
	s_ashr_i32 s13, s12, 31
	s_mov_b32 m0, s29
	s_nop 0
	global_load_lds_dwordx4 v132, s[14:15]
	s_lshl_b64 s[12:13], s[12:13], 12
	s_mov_b32 m0, s30
	s_nop 0
	global_load_lds_dwordx4 v133, s[14:15]
	s_add_u32 s12, s21, s12
	s_addc_u32 s13, s22, s13
	s_mov_b32 m0, s31
	s_nop 0
	global_load_lds_dwordx4 v132, s[12:13]
	s_mov_b32 m0, s34
	s_nop 0
	global_load_lds_dwordx4 v133, s[12:13]
	s_and_saveexec_b64 s[18:19], s[38:39]
	s_cbranch_execz .LBB0_593
	s_barrier

.LBB0_629:
	s_ashr_i32 s6, s8, 3
	s_add_i32 s6, s10, s6
	s_ashr_i32 s7, s6, 31
	s_lshr_b32 s7, s7, 26
	s_add_i32 s7, s6, s7
	s_and_b32 s8, s7, 0xffc0
	s_sub_i32 s6, s6, s8
	s_bfe_i32 s8, s6, 0x80000
	s_bfe_u32 s8, s8, 0x3000c
	s_add_i32 s8, s6, s8
	s_bfe_i32 s9, s8, 0x80000
	s_and_b32 s8, s8, 0xf8
	s_sub_i32 s6, s6, s8
	s_sext_i32_i8 s6, s6
	s_lshl_b32 s7, s7, 5
	s_sext_i32_i16 s9, s9
	s_and_b32 s7, s7, 0xfffff800
	s_lshl_b32 s6, s6, 8
	s_add_i32 s6, s6, s7
	s_lshl_b32 s7, s9, 5
	s_and_b32 s8, s7, 0xffffff00
	s_ashr_i32 s9, s8, 31
	s_lshl_b64 s[10:11], s[8:9], 12
	s_add_u32 s10, s23, s10
	s_addc_u32 s11, s24, s11
	s_ashr_i32 s7, s6, 31
	s_lshl_b64 s[18:19], s[6:7], 12
	s_add_u32 s12, s25, s18
	s_addc_u32 s13, s26, s19
	s_or_b32 s14, s8, 0x80
	s_ashr_i32 s15, s14, 31
	s_mov_b32 m0, s28
	s_nop 0
	global_load_lds_dwordx4 v0, s[10:11]
	s_lshl_b64 s[14:15], s[14:15], 12
	s_mov_b32 m0, s29
	s_nop 0
	global_load_lds_dwordx4 v138, s[10:11]
	s_add_u32 s16, s23, s14
	s_mov_b32 m0, s27
	s_nop 0
	global_load_lds_dwordx4 v0, s[12:13]
	s_addc_u32 s17, s24, s15
	s_or_b32 s14, s6, 0x80
	s_mov_b32 m0, s30
	s_nop 0
	global_load_lds_dwordx4 v138, s[12:13]
	s_ashr_i32 s15, s14, 31
	s_mov_b32 m0, s31
	s_nop 0
	global_load_lds_dwordx4 v0, s[16:17]
	s_lshl_b64 s[14:15], s[14:15], 12
	s_mov_b32 m0, s34
	s_nop 0
	global_load_lds_dwordx4 v138, s[16:17]
	s_add_u32 s14, s25, s14
	s_addc_u32 s15, s26, s15
	s_mov_b32 m0, s35
	s_nop 0
	global_load_lds_dwordx4 v0, s[14:15]
	s_mov_b32 m0, s36
	s_nop 0
	global_load_lds_dwordx4 v138, s[14:15]
	s_and_saveexec_b64 s[20:21], s[38:39]
	s_cbranch_execz .LBB0_631
	s_barrier

.LBB0_663:
	s_ashr_i32 s6, s8, 3
	s_add_i32 s6, s10, s6
	s_ashr_i32 s7, s6, 31
	s_lshr_b32 s7, s7, 26
	s_add_i32 s7, s6, s7
	s_and_b32 s8, s7, 0xffc0
	s_sub_i32 s6, s6, s8
	s_bfe_i32 s8, s6, 0x80000
	s_bfe_u32 s8, s8, 0x3000c
	s_add_i32 s8, s6, s8
	s_bfe_i32 s9, s8, 0x80000
	s_and_b32 s8, s8, 0xf8
	s_sub_i32 s6, s6, s8
	s_sext_i32_i8 s6, s6
	s_lshl_b32 s7, s7, 5
	s_sext_i32_i16 s9, s9
	s_and_b32 s7, s7, 0xfffff800
	s_lshl_b32 s6, s6, 8
	s_add_i32 s8, s6, s7
	s_lshl_b32 s6, s9, 5
	s_and_b32 s6, s6, 0xffffff00
	s_ashr_i32 s7, s6, 31
	s_lshl_b64 s[10:11], s[6:7], 12
	s_add_u32 s10, s23, s10
	s_addc_u32 s11, s24, s11
	s_ashr_i32 s9, s8, 31
	s_lshl_b64 s[18:19], s[8:9], 12
	s_add_u32 s12, s0, s18
	s_addc_u32 s13, s1, s19
	s_or_b32 s14, s6, 0x80
	s_ashr_i32 s15, s14, 31
	s_mov_b32 m0, s26
	s_nop 0
	global_load_lds_dwordx4 v0, s[10:11]
	s_lshl_b64 s[14:15], s[14:15], 12
	s_mov_b32 m0, s27
	s_nop 0
	global_load_lds_dwordx4 v140, s[10:11]
	s_add_u32 s16, s23, s14
	s_mov_b32 m0, s25
	s_nop 0
	global_load_lds_dwordx4 v0, s[12:13]
	s_addc_u32 s17, s24, s15
	s_or_b32 s14, s8, 0x80
	s_mov_b32 m0, s28
	s_nop 0
	global_load_lds_dwordx4 v140, s[12:13]
	s_ashr_i32 s15, s14, 31
	s_mov_b32 m0, s29
	s_nop 0
	global_load_lds_dwordx4 v0, s[16:17]
	s_lshl_b64 s[14:15], s[14:15], 12
	s_mov_b32 m0, s30
	s_nop 0
	global_load_lds_dwordx4 v140, s[16:17]
	s_add_u32 s14, s0, s14
	s_addc_u32 s15, s1, s15
	s_mov_b32 m0, s31
	s_nop 0
	global_load_lds_dwordx4 v0, s[14:15]
	s_mov_b32 m0, s34
	s_nop 0
	global_load_lds_dwordx4 v140, s[14:15]
	s_and_saveexec_b64 s[20:21], s[38:39]
	s_cbranch_execz .LBB0_665
	s_barrier
